# B loops: q blocks 10,11 fetched at the head of the QK block instead of in its LDS-saturated tail
# baseline (speedup 1.0000x reference)
; __device__ __forceinline__ void qkt12_roll(f32x16& p0, f32x16& p1, const f32x16& negm, int kb, int qa, const bf16x8* qr) {
;   const int a0 = kb ^ (0 << 5); const bf16x8 x0 = lds_rd128<0>(a0), y0 = lds_rd128<12288>(a0);
;   const int a1 = kb ^ (1 << 5); const bf16x8 x1 = lds_rd128<0>(a1), y1 = lds_rd128<12288>(a1);
;   asm volatile("s_waitcnt lgkmcnt(2)" ::: "memory"); SBAR();
;   p0 = __builtin_amdgcn_mfma_f32_32x32x16_bf16(x0, qr[0], negm, 0, 0, 0); p1 = __builtin_amdgcn_mfma_f32_32x32x16_bf16(y0, qr[0], negm, 0, 0, 0);
;   const int a2 = kb ^ (2 << 5); const bf16x8 x2 = lds_rd128<0>(a2), y2 = lds_rd128<12288>(a2);
;   asm volatile("s_waitcnt lgkmcnt(2)" ::: "memory"); SBAR();
;   p0 = __builtin_amdgcn_mfma_f32_32x32x16_bf16(x1, qr[1], p0, 0, 0, 0); p1 = __builtin_amdgcn_mfma_f32_32x32x16_bf16(y1, qr[1], p1, 0, 0, 0);
;   const int a3 = kb ^ (3 << 5); const bf16x8 x3 = lds_rd128<0>(a3), y3 = lds_rd128<12288>(a3);
;   asm volatile("s_waitcnt lgkmcnt(2)" ::: "memory"); SBAR();
;   p0 = __builtin_amdgcn_mfma_f32_32x32x16_bf16(x2, qr[2], p0, 0, 0, 0); p1 = __builtin_amdgcn_mfma_f32_32x32x16_bf16(y2, qr[2], p1, 0, 0, 0);
;   const int a4 = kb ^ (0 << 5); const bf16x8 x4 = lds_rd128<128>(a4), y4 = lds_rd128<12416>(a4);
;   asm volatile("s_waitcnt lgkmcnt(2)" ::: "memory"); SBAR();
;   p0 = __builtin_amdgcn_mfma_f32_32x32x16_bf16(x3, qr[3], p0, 0, 0, 0); p1 = __builtin_amdgcn_mfma_f32_32x32x16_bf16(y3, qr[3], p1, 0, 0, 0);
;   const int a5 = kb ^ (1 << 5); const bf16x8 x5 = lds_rd128<128>(a5), y5 = lds_rd128<12416>(a5);
;   asm volatile("s_waitcnt lgkmcnt(2)" ::: "memory"); SBAR();
;   p0 = __builtin_amdgcn_mfma_f32_32x32x16_bf16(x4, qr[4], p0, 0, 0, 0); p1 = __builtin_amdgcn_mfma_f32_32x32x16_bf16(y4, qr[4], p1, 0, 0, 0);
;   const int a6 = kb ^ (2 << 5); const bf16x8 x6 = lds_rd128<128>(a6), y6 = lds_rd128<12416>(a6);
;   asm volatile("s_waitcnt lgkmcnt(2)" ::: "memory"); SBAR();
;   p0 = __builtin_amdgcn_mfma_f32_32x32x16_bf16(x5, qr[5], p0, 0, 0, 0); p1 = __builtin_amdgcn_mfma_f32_32x32x16_bf16(y5, qr[5], p1, 0, 0, 0);
;   const int a7 = kb ^ (3 << 5); const bf16x8 x7 = lds_rd128<128>(a7), y7 = lds_rd128<12416>(a7);
;   asm volatile("s_waitcnt lgkmcnt(2)" ::: "memory"); SBAR();
;   p0 = __builtin_amdgcn_mfma_f32_32x32x16_bf16(x6, qr[6], p0, 0, 0, 0); p1 = __builtin_amdgcn_mfma_f32_32x32x16_bf16(y6, qr[6], p1, 0, 0, 0);
.Lmy_negm_back_0:
	ds_read_b128 v[178:181], v199 offset:0x800
	ds_read_b128 v[230:233], v199 offset:0xc00
	ds_read_b128 v[82:85], v221 offset:0
	ds_read_b128 v[162:165], v221 offset:0x3000
	ds_read_b128 v[166:169], v220 offset:0
	ds_read_b128 v[170:173], v220 offset:0x3000
	s_waitcnt lgkmcnt(2)
	s_nop 1
	v_mfma_f32_32x32x16_bf16 v[98:113], v[82:85], v[142:145], v[66:81]
	v_mfma_f32_32x32x16_bf16 v[82:97], v[162:165], v[142:145], v[66:81]
	ds_read_b128 v[162:165], v219 offset:0
	ds_read_b128 v[174:177], v219 offset:0x3000
	s_waitcnt lgkmcnt(2)
	v_mfma_f32_32x32x16_bf16 v[98:113], v[166:169], v[138:141], v[98:113]
	ds_read_b128 v[166:169], v218 offset:0
	v_mfma_f32_32x32x16_bf16 v[82:97], v[170:173], v[138:141], v[82:97]
	ds_read_b128 v[170:173], v218 offset:0x3000
	s_waitcnt lgkmcnt(2)
	v_mfma_f32_32x32x16_bf16 v[98:113], v[162:165], v[134:137], v[98:113]
	ds_read_b128 v[162:165], v221 offset:0x80
	v_mfma_f32_32x32x16_bf16 v[82:97], v[174:177], v[134:137], v[82:97]
	ds_read_b128 v[174:177], v221 offset:0x3080
	s_waitcnt lgkmcnt(2)
	v_mfma_f32_32x32x16_bf16 v[98:113], v[166:169], v[130:133], v[98:113]
	ds_read_b128 v[166:169], v220 offset:0x80
	v_mfma_f32_32x32x16_bf16 v[82:97], v[170:173], v[130:133], v[82:97]
	ds_read_b128 v[170:173], v220 offset:0x3080
	s_waitcnt lgkmcnt(2)
	v_mfma_f32_32x32x16_bf16 v[98:113], v[162:165], v[126:129], v[98:113]
	ds_read_b128 v[162:165], v219 offset:0x80
	v_mfma_f32_32x32x16_bf16 v[82:97], v[174:177], v[126:129], v[82:97]
	ds_read_b128 v[174:177], v219 offset:0x3080
	s_waitcnt lgkmcnt(2)
	v_mfma_f32_32x32x16_bf16 v[98:113], v[166:169], v[122:125], v[98:113]
	ds_read_b128 v[166:169], v218 offset:0x80
	v_mfma_f32_32x32x16_bf16 v[82:97], v[170:173], v[122:125], v[82:97]
	ds_read_b128 v[170:173], v218 offset:0x3080
	s_waitcnt lgkmcnt(2)
	v_mfma_f32_32x32x16_bf16 v[98:113], v[162:165], v[118:121], v[98:113]
	ds_read_b128 v[162:165], v221 offset:0x100
	v_mfma_f32_32x32x16_bf16 v[82:97], v[174:177], v[118:121], v[82:97]
	ds_read_b128 v[174:177], v221 offset:0x3100
	s_waitcnt lgkmcnt(2)
	v_mfma_f32_32x32x16_bf16 v[98:113], v[166:169], v[114:117], v[98:113]
	ds_read_b128 v[166:169], v220 offset:0x100
	v_mfma_f32_32x32x16_bf16 v[82:97], v[170:173], v[114:117], v[82:97]
	ds_read_b128 v[170:173], v220 offset:0x3100
	s_waitcnt lgkmcnt(2)
	v_mfma_f32_32x32x16_bf16 v[98:113], v[162:165], v[192:195], v[98:113]
	ds_read_b128 v[162:165], v219 offset:0x100
	v_mfma_f32_32x32x16_bf16 v[82:97], v[174:177], v[192:195], v[82:97]
	ds_read_b128 v[174:177], v219 offset:0x3100
	s_waitcnt lgkmcnt(2)
	v_mfma_f32_32x32x16_bf16 v[98:113], v[166:169], v[202:205], v[98:113]
	ds_read_b128 v[166:169], v218 offset:0x100
	v_mfma_f32_32x32x16_bf16 v[82:97], v[170:173], v[202:205], v[82:97]
	ds_read_b128 v[170:173], v218 offset:0x3100
	s_waitcnt lgkmcnt(2)
	v_mfma_f32_32x32x16_bf16 v[98:113], v[162:165], v[178:181], v[98:113]
	s_waitcnt lgkmcnt(0)
	v_mfma_f32_32x32x16_bf16 v[82:97], v[174:177], v[178:181], v[82:97]
	v_mfma_f32_32x32x16_bf16 v[98:113], v[166:169], v[230:233], v[98:113]
	v_mfma_f32_32x32x16_bf16 v[82:97], v[170:173], v[230:233], v[82:97]
	s_nop 10
	v_max_f32_e32 v162, v98, v102
	v_max_f32_e32 v163, v99, v103
	v_max_f32_e32 v164, v101, v105
	v_max3_f32 v165, v100, v104, v108
	v_max3_f32 v164, v164, v109, v113
	v_max3_f32 v162, v162, v106, v110
	v_max3_f32 v163, v163, v107, v111
	v_max3_f32 v165, v165, v112, v84
	v_max3_f32 v164, v164, v85, v89
	v_max3_f32 v162, v162, v82, v86
	v_max3_f32 v163, v163, v83, v87
	v_max3_f32 v165, v165, v88, v92
	v_max3_f32 v164, v164, v93, v97
	v_max3_f32 v162, v162, v90, v94
	v_max3_f32 v163, v163, v91, v95
	v_max3_f32 v164, v165, v96, v164
	v_max3_f32 v162, v162, v163, v164
	v_cmp_ge_f32_e32 vcc, s48, v162
	s_cmp_eq_u64 vcc, exec
	s_cbranch_scc0 .LBB0_374
	v_mov_b32_e32 v228, v226
	v_mov_b32_e32 v227, 1.0

; __device__ __forceinline__ void qkt12_roll(f32x16& p0, f32x16& p1, const f32x16& negm, int kb, int qa, const bf16x8* qr) {
;   const int a0 = kb ^ (0 << 5); const bf16x8 x0 = lds_rd128<0>(a0), y0 = lds_rd128<12288>(a0);
;   const int a1 = kb ^ (1 << 5); const bf16x8 x1 = lds_rd128<0>(a1), y1 = lds_rd128<12288>(a1);
;   asm volatile("s_waitcnt lgkmcnt(2)" ::: "memory"); SBAR();
;   p0 = __builtin_amdgcn_mfma_f32_32x32x16_bf16(x0, qr[0], negm, 0, 0, 0); p1 = __builtin_amdgcn_mfma_f32_32x32x16_bf16(y0, qr[0], negm, 0, 0, 0);
;   const int a2 = kb ^ (2 << 5); const bf16x8 x2 = lds_rd128<0>(a2), y2 = lds_rd128<12288>(a2);
;   asm volatile("s_waitcnt lgkmcnt(2)" ::: "memory"); SBAR();
;   p0 = __builtin_amdgcn_mfma_f32_32x32x16_bf16(x1, qr[1], p0, 0, 0, 0); p1 = __builtin_amdgcn_mfma_f32_32x32x16_bf16(y1, qr[1], p1, 0, 0, 0);
;   const int a3 = kb ^ (3 << 5); const bf16x8 x3 = lds_rd128<0>(a3), y3 = lds_rd128<12288>(a3);
;   asm volatile("s_waitcnt lgkmcnt(2)" ::: "memory"); SBAR();
;   p0 = __builtin_amdgcn_mfma_f32_32x32x16_bf16(x2, qr[2], p0, 0, 0, 0); p1 = __builtin_amdgcn_mfma_f32_32x32x16_bf16(y2, qr[2], p1, 0, 0, 0);
;   const int a4 = kb ^ (0 << 5); const bf16x8 x4 = lds_rd128<128>(a4), y4 = lds_rd128<12416>(a4);
;   asm volatile("s_waitcnt lgkmcnt(2)" ::: "memory"); SBAR();
;   p0 = __builtin_amdgcn_mfma_f32_32x32x16_bf16(x3, qr[3], p0, 0, 0, 0); p1 = __builtin_amdgcn_mfma_f32_32x32x16_bf16(y3, qr[3], p1, 0, 0, 0);
;   const int a5 = kb ^ (1 << 5); const bf16x8 x5 = lds_rd128<128>(a5), y5 = lds_rd128<12416>(a5);
;   asm volatile("s_waitcnt lgkmcnt(2)" ::: "memory"); SBAR();
;   p0 = __builtin_amdgcn_mfma_f32_32x32x16_bf16(x4, qr[4], p0, 0, 0, 0); p1 = __builtin_amdgcn_mfma_f32_32x32x16_bf16(y4, qr[4], p1, 0, 0, 0);
;   const int a6 = kb ^ (2 << 5); const bf16x8 x6 = lds_rd128<128>(a6), y6 = lds_rd128<12416>(a6);
;   asm volatile("s_waitcnt lgkmcnt(2)" ::: "memory"); SBAR();
;   p0 = __builtin_amdgcn_mfma_f32_32x32x16_bf16(x5, qr[5], p0, 0, 0, 0); p1 = __builtin_amdgcn_mfma_f32_32x32x16_bf16(y5, qr[5], p1, 0, 0, 0);
;   const int a7 = kb ^ (3 << 5); const bf16x8 x7 = lds_rd128<128>(a7), y7 = lds_rd128<12416>(a7);
;   asm volatile("s_waitcnt lgkmcnt(2)" ::: "memory"); SBAR();
;   p0 = __builtin_amdgcn_mfma_f32_32x32x16_bf16(x6, qr[6], p0, 0, 0, 0); p1 = __builtin_amdgcn_mfma_f32_32x32x16_bf16(y6, qr[6], p1, 0, 0, 0);
.Lmy_negm_back_1:
	ds_read_b128 v[178:181], v199 offset:0x800
	ds_read_b128 v[232:235], v199 offset:0xc00
	ds_read_b128 v[66:69], v209 offset:0
	ds_read_b128 v[162:165], v209 offset:0x3000
	ds_read_b128 v[166:169], v215 offset:0
	ds_read_b128 v[170:173], v215 offset:0x3000
	s_waitcnt lgkmcnt(2)
	s_nop 1
	v_mfma_f32_32x32x16_bf16 v[98:113], v[66:69], v[142:145], v[82:97]
	v_mfma_f32_32x32x16_bf16 v[66:81], v[162:165], v[142:145], v[82:97]
	ds_read_b128 v[162:165], v216 offset:0
	ds_read_b128 v[174:177], v216 offset:0x3000
	s_waitcnt lgkmcnt(2)
	v_mfma_f32_32x32x16_bf16 v[98:113], v[166:169], v[138:141], v[98:113]
	ds_read_b128 v[166:169], v217 offset:0
	v_mfma_f32_32x32x16_bf16 v[66:81], v[170:173], v[138:141], v[66:81]
	ds_read_b128 v[170:173], v217 offset:0x3000
	s_waitcnt lgkmcnt(2)
	v_mfma_f32_32x32x16_bf16 v[98:113], v[162:165], v[134:137], v[98:113]
	ds_read_b128 v[162:165], v209 offset:0x80
	v_mfma_f32_32x32x16_bf16 v[66:81], v[174:177], v[134:137], v[66:81]
	ds_read_b128 v[174:177], v209 offset:0x3080
	s_waitcnt lgkmcnt(2)
	v_mfma_f32_32x32x16_bf16 v[98:113], v[166:169], v[130:133], v[98:113]
	ds_read_b128 v[166:169], v215 offset:0x80
	v_mfma_f32_32x32x16_bf16 v[66:81], v[170:173], v[130:133], v[66:81]
	ds_read_b128 v[170:173], v215 offset:0x3080
	s_waitcnt lgkmcnt(2)
	v_mfma_f32_32x32x16_bf16 v[98:113], v[162:165], v[126:129], v[98:113]
	ds_read_b128 v[162:165], v216 offset:0x80
	v_mfma_f32_32x32x16_bf16 v[66:81], v[174:177], v[126:129], v[66:81]
	ds_read_b128 v[174:177], v216 offset:0x3080
	s_waitcnt lgkmcnt(2)
	v_mfma_f32_32x32x16_bf16 v[98:113], v[166:169], v[122:125], v[98:113]
	ds_read_b128 v[166:169], v217 offset:0x80
	v_mfma_f32_32x32x16_bf16 v[66:81], v[170:173], v[122:125], v[66:81]
	ds_read_b128 v[170:173], v217 offset:0x3080
	s_waitcnt lgkmcnt(2)
	v_mfma_f32_32x32x16_bf16 v[98:113], v[162:165], v[118:121], v[98:113]
	ds_read_b128 v[162:165], v209 offset:0x100
	v_mfma_f32_32x32x16_bf16 v[66:81], v[174:177], v[118:121], v[66:81]
	ds_read_b128 v[174:177], v209 offset:0x3100
	s_waitcnt lgkmcnt(2)
	v_mfma_f32_32x32x16_bf16 v[98:113], v[166:169], v[114:117], v[98:113]
	ds_read_b128 v[166:169], v215 offset:0x100
	v_mfma_f32_32x32x16_bf16 v[66:81], v[170:173], v[114:117], v[66:81]
	ds_read_b128 v[170:173], v215 offset:0x3100
	s_waitcnt lgkmcnt(2)
	v_mfma_f32_32x32x16_bf16 v[98:113], v[162:165], v[192:195], v[98:113]
	ds_read_b128 v[162:165], v216 offset:0x100
	v_mfma_f32_32x32x16_bf16 v[66:81], v[174:177], v[192:195], v[66:81]
	ds_read_b128 v[174:177], v216 offset:0x3100
	s_waitcnt lgkmcnt(2)
	v_mfma_f32_32x32x16_bf16 v[98:113], v[166:169], v[202:205], v[98:113]
	ds_read_b128 v[166:169], v217 offset:0x100
	v_mfma_f32_32x32x16_bf16 v[66:81], v[170:173], v[202:205], v[66:81]
	ds_read_b128 v[170:173], v217 offset:0x3100
	s_waitcnt lgkmcnt(2)
	v_mfma_f32_32x32x16_bf16 v[98:113], v[162:165], v[178:181], v[98:113]
	s_waitcnt lgkmcnt(0)
	v_mfma_f32_32x32x16_bf16 v[66:81], v[174:177], v[178:181], v[66:81]
	v_mfma_f32_32x32x16_bf16 v[98:113], v[166:169], v[232:235], v[98:113]
	v_mfma_f32_32x32x16_bf16 v[66:81], v[170:173], v[232:235], v[66:81]
	s_nop 10
	v_max_f32_e32 v162, v98, v102
	v_max_f32_e32 v163, v99, v103
	v_max_f32_e32 v164, v101, v105
	v_max3_f32 v165, v100, v104, v108
	v_max3_f32 v164, v164, v109, v113
	v_max3_f32 v162, v162, v106, v110
	v_max3_f32 v163, v163, v107, v111
	v_max3_f32 v165, v165, v112, v68
	v_max3_f32 v164, v164, v69, v73
	v_max3_f32 v162, v162, v66, v70
	v_max3_f32 v163, v163, v67, v71
	v_max3_f32 v165, v165, v72, v76
	v_max3_f32 v164, v164, v77, v81
	v_max3_f32 v162, v162, v74, v78
	v_max3_f32 v163, v163, v75, v79
	v_max3_f32 v164, v165, v80, v164
	v_max3_f32 v162, v162, v163, v164
	v_cmp_ge_f32_e32 vcc, s48, v162
	s_cmp_eq_u64 vcc, exec
	v_mov_b32_e32 v223, 1.0
	s_cbranch_scc0 .LBB0_375
	v_mov_b32_e32 v226, v228

; __device__ __forceinline__ void qkt12_roll(f32x16& p0, f32x16& p1, const f32x16& negm, int kb, int qa, const bf16x8* qr) {
;   const int a0 = kb ^ (0 << 5); const bf16x8 x0 = lds_rd128<0>(a0), y0 = lds_rd128<12288>(a0);
;   const int a1 = kb ^ (1 << 5); const bf16x8 x1 = lds_rd128<0>(a1), y1 = lds_rd128<12288>(a1);
;   asm volatile("s_waitcnt lgkmcnt(2)" ::: "memory"); SBAR();
;   p0 = __builtin_amdgcn_mfma_f32_32x32x16_bf16(x0, qr[0], negm, 0, 0, 0); p1 = __builtin_amdgcn_mfma_f32_32x32x16_bf16(y0, qr[0], negm, 0, 0, 0);
;   const int a2 = kb ^ (2 << 5); const bf16x8 x2 = lds_rd128<0>(a2), y2 = lds_rd128<12288>(a2);
;   asm volatile("s_waitcnt lgkmcnt(2)" ::: "memory"); SBAR();
;   p0 = __builtin_amdgcn_mfma_f32_32x32x16_bf16(x1, qr[1], p0, 0, 0, 0); p1 = __builtin_amdgcn_mfma_f32_32x32x16_bf16(y1, qr[1], p1, 0, 0, 0);
;   const int a3 = kb ^ (3 << 5); const bf16x8 x3 = lds_rd128<0>(a3), y3 = lds_rd128<12288>(a3);
;   asm volatile("s_waitcnt lgkmcnt(2)" ::: "memory"); SBAR();
;   p0 = __builtin_amdgcn_mfma_f32_32x32x16_bf16(x2, qr[2], p0, 0, 0, 0); p1 = __builtin_amdgcn_mfma_f32_32x32x16_bf16(y2, qr[2], p1, 0, 0, 0);
;   const int a4 = kb ^ (0 << 5); const bf16x8 x4 = lds_rd128<128>(a4), y4 = lds_rd128<12416>(a4);
;   asm volatile("s_waitcnt lgkmcnt(2)" ::: "memory"); SBAR();
;   p0 = __builtin_amdgcn_mfma_f32_32x32x16_bf16(x3, qr[3], p0, 0, 0, 0); p1 = __builtin_amdgcn_mfma_f32_32x32x16_bf16(y3, qr[3], p1, 0, 0, 0);
;   const int a5 = kb ^ (1 << 5); const bf16x8 x5 = lds_rd128<128>(a5), y5 = lds_rd128<12416>(a5);
;   asm volatile("s_waitcnt lgkmcnt(2)" ::: "memory"); SBAR();
;   p0 = __builtin_amdgcn_mfma_f32_32x32x16_bf16(x4, qr[4], p0, 0, 0, 0); p1 = __builtin_amdgcn_mfma_f32_32x32x16_bf16(y4, qr[4], p1, 0, 0, 0);
;   const int a6 = kb ^ (2 << 5); const bf16x8 x6 = lds_rd128<128>(a6), y6 = lds_rd128<12416>(a6);
;   asm volatile("s_waitcnt lgkmcnt(2)" ::: "memory"); SBAR();
;   p0 = __builtin_amdgcn_mfma_f32_32x32x16_bf16(x5, qr[5], p0, 0, 0, 0); p1 = __builtin_amdgcn_mfma_f32_32x32x16_bf16(y5, qr[5], p1, 0, 0, 0);
;   const int a7 = kb ^ (3 << 5); const bf16x8 x7 = lds_rd128<128>(a7), y7 = lds_rd128<12416>(a7);
;   asm volatile("s_waitcnt lgkmcnt(2)" ::: "memory"); SBAR();
;   p0 = __builtin_amdgcn_mfma_f32_32x32x16_bf16(x6, qr[6], p0, 0, 0, 0); p1 = __builtin_amdgcn_mfma_f32_32x32x16_bf16(y6, qr[6], p1, 0, 0, 0);
.Lmy_negm_skip_0:
	ds_read_b128 v[246:249], v199 offset:0x800
	ds_read_b128 v[250:253], v199 offset:0xc00
	ds_read_b128 v[82:85], v221 offset:0
	ds_read_b128 v[230:233], v221 offset:0x3000
	ds_read_b128 v[234:237], v220 offset:0
	ds_read_b128 v[238:241], v220 offset:0x3000
	s_waitcnt lgkmcnt(2)
	s_nop 1
	v_mfma_f32_32x32x16_bf16 v[114:129], v[82:85], v[158:161], v[98:113]
	v_mfma_f32_32x32x16_bf16 v[82:97], v[230:233], v[158:161], v[98:113]
	ds_read_b128 v[230:233], v219 offset:0
	ds_read_b128 v[242:245], v219 offset:0x3000
	s_waitcnt lgkmcnt(2)
	v_mfma_f32_32x32x16_bf16 v[114:129], v[234:237], v[154:157], v[114:129]
	ds_read_b128 v[234:237], v218 offset:0
	v_mfma_f32_32x32x16_bf16 v[82:97], v[238:241], v[154:157], v[82:97]
	ds_read_b128 v[238:241], v218 offset:0x3000
	s_waitcnt lgkmcnt(2)
	v_mfma_f32_32x32x16_bf16 v[114:129], v[230:233], v[150:153], v[114:129]
	ds_read_b128 v[230:233], v221 offset:0x80
	v_mfma_f32_32x32x16_bf16 v[82:97], v[242:245], v[150:153], v[82:97]
	ds_read_b128 v[242:245], v221 offset:0x3080
	s_waitcnt lgkmcnt(2)
	v_mfma_f32_32x32x16_bf16 v[114:129], v[234:237], v[146:149], v[114:129]
	ds_read_b128 v[234:237], v220 offset:0x80
	v_mfma_f32_32x32x16_bf16 v[82:97], v[238:241], v[146:149], v[82:97]
	ds_read_b128 v[238:241], v220 offset:0x3080
	s_waitcnt lgkmcnt(2)
	v_mfma_f32_32x32x16_bf16 v[114:129], v[230:233], v[142:145], v[114:129]
	ds_read_b128 v[230:233], v219 offset:0x80
	v_mfma_f32_32x32x16_bf16 v[82:97], v[242:245], v[142:145], v[82:97]
	ds_read_b128 v[242:245], v219 offset:0x3080
	s_waitcnt lgkmcnt(2)
	v_mfma_f32_32x32x16_bf16 v[114:129], v[234:237], v[138:141], v[114:129]
	ds_read_b128 v[234:237], v218 offset:0x80
	v_mfma_f32_32x32x16_bf16 v[82:97], v[238:241], v[138:141], v[82:97]
	ds_read_b128 v[238:241], v218 offset:0x3080
	s_waitcnt lgkmcnt(2)
	v_mfma_f32_32x32x16_bf16 v[114:129], v[230:233], v[134:137], v[114:129]
	ds_read_b128 v[230:233], v221 offset:0x100
	v_mfma_f32_32x32x16_bf16 v[82:97], v[242:245], v[134:137], v[82:97]
	ds_read_b128 v[242:245], v221 offset:0x3100
	s_waitcnt lgkmcnt(2)
	v_mfma_f32_32x32x16_bf16 v[114:129], v[234:237], v[130:133], v[114:129]
	ds_read_b128 v[234:237], v220 offset:0x100
	v_mfma_f32_32x32x16_bf16 v[82:97], v[238:241], v[130:133], v[82:97]
	ds_read_b128 v[238:241], v220 offset:0x3100
	s_waitcnt lgkmcnt(2)
	v_mfma_f32_32x32x16_bf16 v[114:129], v[230:233], v[192:195], v[114:129]
	ds_read_b128 v[230:233], v219 offset:0x100
	v_mfma_f32_32x32x16_bf16 v[82:97], v[242:245], v[192:195], v[82:97]
	ds_read_b128 v[242:245], v219 offset:0x3100
	s_waitcnt lgkmcnt(2)
	v_mfma_f32_32x32x16_bf16 v[114:129], v[234:237], v[202:205], v[114:129]
	ds_read_b128 v[234:237], v218 offset:0x100
	v_mfma_f32_32x32x16_bf16 v[82:97], v[238:241], v[202:205], v[82:97]
	ds_read_b128 v[238:241], v218 offset:0x3100
	s_waitcnt lgkmcnt(2)
	v_mfma_f32_32x32x16_bf16 v[114:129], v[230:233], v[246:249], v[114:129]
	s_waitcnt lgkmcnt(0)
	v_mfma_f32_32x32x16_bf16 v[82:97], v[242:245], v[246:249], v[82:97]
	v_mfma_f32_32x32x16_bf16 v[114:129], v[234:237], v[250:253], v[114:129]
	v_mfma_f32_32x32x16_bf16 v[82:97], v[238:241], v[250:253], v[82:97]
	v_exp_f32_e32 v66, v66
	v_exp_f32_e32 v67, v67
	v_exp_f32_e32 v68, v68
	v_exp_f32_e32 v69, v69
	v_exp_f32_e32 v70, v70
	v_exp_f32_e32 v71, v71
	v_exp_f32_e32 v72, v72
	v_exp_f32_e32 v73, v73
	v_add_f32_e32 v166, v168, v176
	v_add_f32_e32 v179, v175, v178
	v_add_f32_e32 v180, v169, v167
	v_add_f32_e32 v181, v174, v177
	v_exp_f32_e32 v74, v74
	v_exp_f32_e32 v75, v75
	v_exp_f32_e32 v76, v76
	v_exp_f32_e32 v77, v77
	v_add_f32_e32 v166, v170, v166
	v_add_f32_e32 v179, v173, v179
	v_add_f32_e32 v180, v165, v180
	v_add_f32_e32 v181, v171, v181
	v_exp_f32_e32 v78, v78
	v_exp_f32_e32 v79, v79
	v_exp_f32_e32 v80, v80
	v_exp_f32_e32 v81, v81
	v_add_f32_e32 v166, v163, v166
	v_add_f32_e32 v179, v172, v179
	v_add_f32_e32 v180, v162, v180
	v_add_f32_e32 v181, v164, v181
	v_add_f32_e32 v166, v66, v166
	v_add_f32_e32 v179, v67, v179
	v_add_f32_e32 v180, v68, v180
	v_add_f32_e32 v181, v69, v181
	v_add_f32_e32 v166, v70, v166
	v_add_f32_e32 v179, v71, v179
	v_add_f32_e32 v180, v72, v180
	v_add_f32_e32 v181, v73, v181
	v_add_f32_e32 v166, v74, v166
	v_add_f32_e32 v179, v75, v179
	v_add_f32_e32 v180, v76, v180
	v_add_f32_e32 v181, v77, v181
	v_add_f32_e32 v166, v78, v166
	v_add_f32_e32 v179, v79, v179
	v_add_f32_e32 v180, v80, v180
	v_add_f32_e32 v181, v81, v181
	v_add_f32_e32 v166, v166, v179
	v_add_f32_e32 v179, v180, v181
	v_add_f32_e32 v223, v166, v179
	v_mov_b32_e32 v224, v223
	v_cvt_pk_bf16_f32 v166, v176, v178
	v_cvt_pk_bf16_f32 v167, v167, v177
	v_cvt_pk_bf16_f32 v168, v168, v175
	s_nop 1
	v_permlane32_swap_b32_e32 v223, v224
	v_cvt_pk_bf16_f32 v169, v169, v174
	v_cvt_pk_bf16_f32 v170, v170, v173
	v_cvt_pk_bf16_f32 v171, v165, v171
	v_cvt_pk_bf16_f32 v172, v163, v172
	v_cvt_pk_bf16_f32 v173, v162, v164
	v_cvt_pk_bf16_f32 v174, v66, v67
	v_cvt_pk_bf16_f32 v175, v68, v69
	v_cvt_pk_bf16_f32 v176, v70, v71
	v_cvt_pk_bf16_f32 v177, v72, v73
	v_cvt_pk_bf16_f32 v178, v74, v75
	v_cvt_pk_bf16_f32 v179, v76, v77
	v_cvt_pk_bf16_f32 v180, v78, v79
	v_cvt_pk_bf16_f32 v181, v80, v81
	v_lshl_add_u64 v[190:191], s[42:43], 0, v[188:189]
	v_add_co_u32_e32 v70, vcc, s49, v190
	v_lshl_add_u64 v[196:197], s[42:43], 0, v[186:187]
	s_nop 0
	v_addc_co_u32_e32 v71, vcc, 0, v191, vcc
	v_add_co_u32_e32 v74, vcc, s28, v190
	s_nop 1
	v_addc_co_u32_e32 v75, vcc, 0, v191, vcc
	global_load_dwordx4 v[66:69], v[70:71], off offset:256
	s_nop 0
	global_load_dwordx4 v[70:73], v[70:71], off
	s_nop 0
	global_load_dwordx4 v[78:81], v[74:75], off offset:256
	s_nop 0
	global_load_dwordx4 v[74:77], v[74:75], off
	v_add_co_u32_e32 v162, vcc, s68, v196
	s_nop 1
	v_addc_co_u32_e32 v163, vcc, 0, v197, vcc
	global_load_dwordx4 v[162:165], v[162:163], off
	ds_read_b64_tr_b16 v[230:231], v201 offset:0
	ds_read_b64_tr_b16 v[232:233], v201 offset:0x800
	ds_read_b64_tr_b16 v[234:235], v201 offset:0x1000
	ds_read_b64_tr_b16 v[236:237], v201 offset:0x1800
	ds_read_b64_tr_b16 v[238:239], v201 offset:0x2000
	ds_read_b64_tr_b16 v[240:241], v201 offset:0x2800
	ds_read_b64_tr_b16 v[242:243], v201 offset:0x3000
	ds_read_b64_tr_b16 v[244:245], v201 offset:0x3800
	ds_read_b64_tr_b16 v[246:247], v201 offset:0x200
	ds_read_b64_tr_b16 v[248:249], v201 offset:0xa00
	s_waitcnt lgkmcnt(8)
; __device__ __forceinline__ void pv_d0(f32x16* o, int vb, bf16x8 pa0, bf16x8 pa1, bf16x8 pa2, bf16x8 pa3) {
;     ...
;   const s16x4 l0 = tr_read<v_rd_off(0, 0, 0)>(vb), h0 = tr_read<v_rd_off(0, 0, 1)>(vb);
;   const s16x4 l1 = tr_read<v_rd_off(0, 1, 0)>(vb), h1 = tr_read<v_rd_off(0, 1, 1)>(vb);
;   const s16x4 l2 = tr_read<v_rd_off(0, 2, 0)>(vb), h2 = tr_read<v_rd_off(0, 2, 1)>(vb);
;   const s16x4 l3 = tr_read<v_rd_off(0, 3, 0)>(vb), h3 = tr_read<v_rd_off(0, 3, 1)>(vb);
;   const s16x4 l4 = tr_read<v_rd_off(1, 0, 0)>(vb), h4 = tr_read<v_rd_off(1, 0, 1)>(vb);
;   asm volatile("s_waitcnt lgkmcnt(8)" ::: "memory"); SBAR();
;   o[0] = __builtin_amdgcn_mfma_f32_32x32x16_bf16(pa0, PK(l0, h0), o[0], 0, 0, 0);
;   const s16x4 l5 = tr_read<v_rd_off(1, 1, 0)>(vb), h5 = tr_read<v_rd_off(1, 1, 1)>(vb);
;   asm volatile("s_waitcnt lgkmcnt(8)" ::: "memory"); SBAR();
;   o[0] = __builtin_amdgcn_mfma_f32_32x32x16_bf16(pa1, PK(l1, h1), o[0], 0, 0, 0);
;   const s16x4 l6 = tr_read<v_rd_off(1, 2, 0)>(vb), h6 = tr_read<v_rd_off(1, 2, 1)>(vb);
;   asm volatile("s_waitcnt lgkmcnt(8)" ::: "memory"); SBAR();
;   o[0] = __builtin_amdgcn_mfma_f32_32x32x16_bf16(pa2, PK(l2, h2), o[0], 0, 0, 0);
;   const s16x4 l7 = tr_read<v_rd_off(1, 3, 0)>(vb), h7 = tr_read<v_rd_off(1, 3, 1)>(vb);
;   asm volatile("s_waitcnt lgkmcnt(8)" ::: "memory"); SBAR();
;   o[0] = __builtin_amdgcn_mfma_f32_32x32x16_bf16(pa3, PK(l3, h3), o[0], 0, 0, 0);
;   const s16x4 l8 = tr_read<v_rd_off(2, 0, 0)>(vb), h8 = tr_read<v_rd_off(2, 0, 1)>(vb);
;   asm volatile("s_waitcnt lgkmcnt(8)" ::: "memory"); SBAR();
;   o[1] = __builtin_amdgcn_mfma_f32_32x32x16_bf16(pa0, PK(l4, h4), o[1], 0, 0, 0);
;   const s16x4 l9 = tr_read<v_rd_off(2, 1, 0)>(vb), h9 = tr_read<v_rd_off(2, 1, 1)>(vb);
;   asm volatile("s_waitcnt lgkmcnt(8)" ::: "memory"); SBAR();
;   o[1] = __builtin_amdgcn_mfma_f32_32x32x16_bf16(pa1, PK(l5, h5), o[1], 0, 0, 0);
;   const s16x4 l10 = tr_read<v_rd_off(2, 2, 0)>(vb), h10 = tr_read<v_rd_off(2, 2, 1)>(vb);
;   asm volatile("s_waitcnt lgkmcnt(8)" ::: "memory"); SBAR();
;   o[1] = __builtin_amdgcn_mfma_f32_32x32x16_bf16(pa2, PK(l6, h6), o[1], 0, 0, 0);
;   const s16x4 l11 = tr_read<v_rd_off(2, 3, 0)>(vb), h11 = tr_read<v_rd_off(2, 3, 1)>(vb);
;   asm volatile("s_waitcnt lgkmcnt(8)" ::: "memory"); SBAR();
;   o[1] = __builtin_amdgcn_mfma_f32_32x32x16_bf16(pa3, PK(l7, h7), o[1], 0, 0, 0);
	s_nop 0
	v_mfma_f32_32x32x16_bf16 v[2:17], v[166:169], v[230:233], v[2:17]
	ds_read_b64_tr_b16 v[230:231], v201 offset:0x1200
	ds_read_b64_tr_b16 v[232:233], v201 offset:0x1a00
	s_waitcnt lgkmcnt(8)
	v_mfma_f32_32x32x16_bf16 v[2:17], v[170:173], v[234:237], v[2:17]
	ds_read_b64_tr_b16 v[234:235], v201 offset:0x2200
	ds_read_b64_tr_b16 v[236:237], v201 offset:0x2a00
	s_waitcnt lgkmcnt(8)
	v_mfma_f32_32x32x16_bf16 v[2:17], v[174:177], v[238:241], v[2:17]
	ds_read_b64_tr_b16 v[238:239], v201 offset:0x3200
	ds_read_b64_tr_b16 v[240:241], v201 offset:0x3a00
	s_waitcnt lgkmcnt(8)
	v_mfma_f32_32x32x16_bf16 v[2:17], v[178:181], v[242:245], v[2:17]
	ds_read_b64_tr_b16 v[242:243], v201 offset:0x400
	ds_read_b64_tr_b16 v[244:245], v201 offset:0xc00
	s_waitcnt lgkmcnt(8)
	v_mfma_f32_32x32x16_bf16 v[50:65], v[166:169], v[246:249], v[50:65]
	ds_read_b64_tr_b16 v[246:247], v201 offset:0x1400
	ds_read_b64_tr_b16 v[248:249], v201 offset:0x1c00
	s_waitcnt lgkmcnt(8)
	v_mfma_f32_32x32x16_bf16 v[50:65], v[170:173], v[230:233], v[50:65]
	ds_read_b64_tr_b16 v[230:231], v201 offset:0x2400
	ds_read_b64_tr_b16 v[232:233], v201 offset:0x2c00
	s_waitcnt lgkmcnt(8)
	v_mfma_f32_32x32x16_bf16 v[50:65], v[174:177], v[234:237], v[50:65]
	ds_read_b64_tr_b16 v[234:235], v201 offset:0x3400
	ds_read_b64_tr_b16 v[236:237], v201 offset:0x3c00
	s_waitcnt lgkmcnt(8)
	v_mfma_f32_32x32x16_bf16 v[50:65], v[178:181], v[238:241], v[50:65]
	ds_read_b64_tr_b16 v[238:239], v201 offset:0x600
	ds_read_b64_tr_b16 v[240:241], v201 offset:0xe00
	s_waitcnt lgkmcnt(8)
	v_mfma_f32_32x32x16_bf16 v[34:49], v[166:169], v[242:245], v[34:49]
	ds_read_b64_tr_b16 v[242:243], v201 offset:0x1600
	ds_read_b64_tr_b16 v[244:245], v201 offset:0x1e00
	s_waitcnt lgkmcnt(8)
	v_mfma_f32_32x32x16_bf16 v[34:49], v[170:173], v[246:249], v[34:49]
	ds_read_b64_tr_b16 v[246:247], v201 offset:0x2600
	ds_read_b64_tr_b16 v[248:249], v201 offset:0x2e00
	s_waitcnt lgkmcnt(8)
	v_mfma_f32_32x32x16_bf16 v[34:49], v[174:177], v[230:233], v[34:49]
	ds_read_b64_tr_b16 v[230:231], v201 offset:0x3600
	ds_read_b64_tr_b16 v[232:233], v201 offset:0x3e00
	s_waitcnt lgkmcnt(8)
	v_mfma_f32_32x32x16_bf16 v[34:49], v[178:181], v[234:237], v[34:49]
	s_waitcnt lgkmcnt(6)
	v_mfma_f32_32x32x16_bf16 v[18:33], v[166:169], v[238:241], v[18:33]
	s_waitcnt lgkmcnt(4)
	v_mfma_f32_32x32x16_bf16 v[18:33], v[170:173], v[242:245], v[18:33]
	s_waitcnt lgkmcnt(2)
	v_mfma_f32_32x32x16_bf16 v[18:33], v[174:177], v[246:249], v[18:33]
	s_waitcnt lgkmcnt(0)
	v_max_f32_e32 v166, v114, v118
	v_max_f32_e32 v167, v115, v119
	v_max_f32_e32 v168, v117, v121
	v_max3_f32 v169, v116, v120, v124
	v_max3_f32 v168, v168, v125, v129
	v_max3_f32 v166, v166, v122, v126
	v_max3_f32 v167, v167, v123, v127
	v_max3_f32 v169, v169, v128, v84
	v_max3_f32 v168, v168, v85, v89
	v_max3_f32 v166, v166, v82, v86
	v_max3_f32 v167, v167, v83, v87
	v_max3_f32 v169, v169, v88, v92
	v_max3_f32 v168, v168, v93, v97
	v_mfma_f32_32x32x16_bf16 v[18:33], v[178:181], v[230:233], v[18:33]
	v_max3_f32 v166, v166, v90, v94
	v_max3_f32 v167, v167, v91, v95
	v_max3_f32 v168, v169, v96, v168
	v_max3_f32 v166, v166, v167, v168
	v_cmp_ge_f32_e32 vcc, s48, v166
	s_cmp_eq_u64 vcc, exec
	s_cbranch_scc0 .LBB0_400
	v_mov_b32_e32 v227, v225
	v_mov_b32_e32 v226, 1.0

; __device__ __forceinline__ void qkt12_roll(f32x16& p0, f32x16& p1, const f32x16& negm, int kb, int qa, const bf16x8* qr) {
;   const int a0 = kb ^ (0 << 5); const bf16x8 x0 = lds_rd128<0>(a0), y0 = lds_rd128<12288>(a0);
;   const int a1 = kb ^ (1 << 5); const bf16x8 x1 = lds_rd128<0>(a1), y1 = lds_rd128<12288>(a1);
;   asm volatile("s_waitcnt lgkmcnt(2)" ::: "memory"); SBAR();
;   p0 = __builtin_amdgcn_mfma_f32_32x32x16_bf16(x0, qr[0], negm, 0, 0, 0); p1 = __builtin_amdgcn_mfma_f32_32x32x16_bf16(y0, qr[0], negm, 0, 0, 0);
;   const int a2 = kb ^ (2 << 5); const bf16x8 x2 = lds_rd128<0>(a2), y2 = lds_rd128<12288>(a2);
;   asm volatile("s_waitcnt lgkmcnt(2)" ::: "memory"); SBAR();
;   p0 = __builtin_amdgcn_mfma_f32_32x32x16_bf16(x1, qr[1], p0, 0, 0, 0); p1 = __builtin_amdgcn_mfma_f32_32x32x16_bf16(y1, qr[1], p1, 0, 0, 0);
;   const int a3 = kb ^ (3 << 5); const bf16x8 x3 = lds_rd128<0>(a3), y3 = lds_rd128<12288>(a3);
;   asm volatile("s_waitcnt lgkmcnt(2)" ::: "memory"); SBAR();
;   p0 = __builtin_amdgcn_mfma_f32_32x32x16_bf16(x2, qr[2], p0, 0, 0, 0); p1 = __builtin_amdgcn_mfma_f32_32x32x16_bf16(y2, qr[2], p1, 0, 0, 0);
;   const int a4 = kb ^ (0 << 5); const bf16x8 x4 = lds_rd128<128>(a4), y4 = lds_rd128<12416>(a4);
;   asm volatile("s_waitcnt lgkmcnt(2)" ::: "memory"); SBAR();
;   p0 = __builtin_amdgcn_mfma_f32_32x32x16_bf16(x3, qr[3], p0, 0, 0, 0); p1 = __builtin_amdgcn_mfma_f32_32x32x16_bf16(y3, qr[3], p1, 0, 0, 0);
;   const int a5 = kb ^ (1 << 5); const bf16x8 x5 = lds_rd128<128>(a5), y5 = lds_rd128<12416>(a5);
;   asm volatile("s_waitcnt lgkmcnt(2)" ::: "memory"); SBAR();
;   p0 = __builtin_amdgcn_mfma_f32_32x32x16_bf16(x4, qr[4], p0, 0, 0, 0); p1 = __builtin_amdgcn_mfma_f32_32x32x16_bf16(y4, qr[4], p1, 0, 0, 0);
;   const int a6 = kb ^ (2 << 5); const bf16x8 x6 = lds_rd128<128>(a6), y6 = lds_rd128<12416>(a6);
;   asm volatile("s_waitcnt lgkmcnt(2)" ::: "memory"); SBAR();
;   p0 = __builtin_amdgcn_mfma_f32_32x32x16_bf16(x5, qr[5], p0, 0, 0, 0); p1 = __builtin_amdgcn_mfma_f32_32x32x16_bf16(y5, qr[5], p1, 0, 0, 0);
;   const int a7 = kb ^ (3 << 5); const bf16x8 x7 = lds_rd128<128>(a7), y7 = lds_rd128<12416>(a7);
;   asm volatile("s_waitcnt lgkmcnt(2)" ::: "memory"); SBAR();
;   p0 = __builtin_amdgcn_mfma_f32_32x32x16_bf16(x6, qr[6], p0, 0, 0, 0); p1 = __builtin_amdgcn_mfma_f32_32x32x16_bf16(y6, qr[6], p1, 0, 0, 0);
.Lmy_negm_skip_1:
	v_exp_f32_e32 v177, v115
	v_exp_f32_e32 v176, v117
	v_exp_f32_e32 v168, v118
	v_exp_f32_e32 v175, v119
	v_exp_f32_e32 v169, v120
	v_exp_f32_e32 v174, v121
	v_exp_f32_e32 v170, v122
	v_exp_f32_e32 v173, v123
	v_exp_f32_e32 v171, v125
	v_exp_f32_e32 v172, v127
	s_waitcnt lgkmcnt(0)
	s_barrier
	ds_read_b128 v[242:245], v199 offset:0x800
	ds_read_b128 v[246:249], v199 offset:0xc00
	ds_read_b128 v[66:69], v209 offset:0
	ds_read_b128 v[178:181], v209 offset:0x3000
	ds_read_b128 v[230:233], v215 offset:0
	ds_read_b128 v[234:237], v215 offset:0x3000
	s_waitcnt lgkmcnt(2)
	s_nop 0
	v_mfma_f32_32x32x16_bf16 v[114:129], v[66:69], v[158:161], v[98:113]
	v_mfma_f32_32x32x16_bf16 v[66:81], v[178:181], v[158:161], v[98:113]
	ds_read_b128 v[178:181], v216 offset:0
	ds_read_b128 v[238:241], v216 offset:0x3000
	s_waitcnt lgkmcnt(2)
	v_mfma_f32_32x32x16_bf16 v[114:129], v[230:233], v[154:157], v[114:129]
	ds_read_b128 v[230:233], v217 offset:0
	v_mfma_f32_32x32x16_bf16 v[66:81], v[234:237], v[154:157], v[66:81]
	ds_read_b128 v[234:237], v217 offset:0x3000
	s_waitcnt lgkmcnt(2)
	v_mfma_f32_32x32x16_bf16 v[114:129], v[178:181], v[150:153], v[114:129]
	ds_read_b128 v[178:181], v209 offset:0x80
	v_mfma_f32_32x32x16_bf16 v[66:81], v[238:241], v[150:153], v[66:81]
	ds_read_b128 v[238:241], v209 offset:0x3080
	s_waitcnt lgkmcnt(2)
	v_mfma_f32_32x32x16_bf16 v[114:129], v[230:233], v[146:149], v[114:129]
	ds_read_b128 v[230:233], v215 offset:0x80
	v_mfma_f32_32x32x16_bf16 v[66:81], v[234:237], v[146:149], v[66:81]
	ds_read_b128 v[234:237], v215 offset:0x3080
	s_waitcnt lgkmcnt(2)
	v_mfma_f32_32x32x16_bf16 v[114:129], v[178:181], v[142:145], v[114:129]
	ds_read_b128 v[178:181], v216 offset:0x80
	v_mfma_f32_32x32x16_bf16 v[66:81], v[238:241], v[142:145], v[66:81]
	ds_read_b128 v[238:241], v216 offset:0x3080
	s_waitcnt lgkmcnt(2)
	v_mfma_f32_32x32x16_bf16 v[114:129], v[230:233], v[138:141], v[114:129]
	ds_read_b128 v[230:233], v217 offset:0x80
	v_mfma_f32_32x32x16_bf16 v[66:81], v[234:237], v[138:141], v[66:81]
	ds_read_b128 v[234:237], v217 offset:0x3080
	s_waitcnt lgkmcnt(2)
	v_mfma_f32_32x32x16_bf16 v[114:129], v[178:181], v[134:137], v[114:129]
	ds_read_b128 v[178:181], v209 offset:0x100
	v_mfma_f32_32x32x16_bf16 v[66:81], v[238:241], v[134:137], v[66:81]
	ds_read_b128 v[238:241], v209 offset:0x3100
	s_waitcnt lgkmcnt(2)
	v_mfma_f32_32x32x16_bf16 v[114:129], v[230:233], v[130:133], v[114:129]
	ds_read_b128 v[230:233], v215 offset:0x100
	v_mfma_f32_32x32x16_bf16 v[66:81], v[234:237], v[130:133], v[66:81]
	ds_read_b128 v[234:237], v215 offset:0x3100
	s_waitcnt lgkmcnt(2)
	v_mfma_f32_32x32x16_bf16 v[114:129], v[178:181], v[192:195], v[114:129]
	ds_read_b128 v[178:181], v216 offset:0x100
	v_mfma_f32_32x32x16_bf16 v[66:81], v[238:241], v[192:195], v[66:81]
	ds_read_b128 v[238:241], v216 offset:0x3100
	s_waitcnt lgkmcnt(2)
	v_mfma_f32_32x32x16_bf16 v[114:129], v[230:233], v[202:205], v[114:129]
	ds_read_b128 v[230:233], v217 offset:0x100
	v_mfma_f32_32x32x16_bf16 v[66:81], v[234:237], v[202:205], v[66:81]
	ds_read_b128 v[234:237], v217 offset:0x3100
	s_waitcnt lgkmcnt(2)
	v_mfma_f32_32x32x16_bf16 v[114:129], v[178:181], v[242:245], v[114:129]
	s_waitcnt lgkmcnt(0)
	v_mfma_f32_32x32x16_bf16 v[66:81], v[238:241], v[242:245], v[66:81]
	v_mfma_f32_32x32x16_bf16 v[114:129], v[230:233], v[246:249], v[114:129]
	v_mfma_f32_32x32x16_bf16 v[66:81], v[234:237], v[246:249], v[66:81]
	v_exp_f32_e32 v82, v82
	v_exp_f32_e32 v83, v83
	v_exp_f32_e32 v84, v84
	v_exp_f32_e32 v85, v85
	v_exp_f32_e32 v86, v86
	v_exp_f32_e32 v87, v87
	v_exp_f32_e32 v88, v88
	v_exp_f32_e32 v89, v89
	v_add_f32_e32 v178, v168, v166
	v_add_f32_e32 v179, v175, v177
	v_add_f32_e32 v180, v169, v167
	v_add_f32_e32 v181, v174, v176
	v_exp_f32_e32 v90, v90
	v_exp_f32_e32 v91, v91
	v_exp_f32_e32 v92, v92
	v_exp_f32_e32 v93, v93
	v_add_f32_e32 v178, v170, v178
	v_add_f32_e32 v179, v173, v179
	v_add_f32_e32 v180, v165, v180
	v_add_f32_e32 v181, v171, v181
	v_exp_f32_e32 v94, v94
	v_exp_f32_e32 v95, v95
	v_exp_f32_e32 v96, v96
	v_exp_f32_e32 v97, v97
	v_add_f32_e32 v178, v163, v178
	v_add_f32_e32 v179, v172, v179
	v_add_f32_e32 v180, v162, v180
	v_add_f32_e32 v181, v164, v181
	v_add_f32_e32 v178, v82, v178
	v_add_f32_e32 v179, v179, v83
	v_add_f32_e32 v180, v180, v84
	v_add_f32_e32 v181, v181, v85
	v_add_f32_e32 v178, v86, v178
	v_add_f32_e32 v179, v87, v179
	v_add_f32_e32 v180, v88, v180
	v_add_f32_e32 v181, v89, v181
	v_add_f32_e32 v178, v90, v178
	v_add_f32_e32 v179, v91, v179
	v_add_f32_e32 v180, v92, v180
	v_add_f32_e32 v181, v93, v181
	v_add_f32_e32 v178, v94, v178
	v_add_f32_e32 v179, v95, v179
	v_add_f32_e32 v180, v96, v180
	v_add_f32_e32 v181, v97, v181
	v_add_f32_e32 v178, v178, v179
	v_add_f32_e32 v179, v180, v181
	v_add_f32_e32 v229, v178, v179
	v_mov_b32_e32 v230, v229
	v_cvt_pk_bf16_f32 v166, v166, v177
	v_cvt_pk_bf16_f32 v167, v167, v176
	v_cvt_pk_bf16_f32 v168, v168, v175
	v_cvt_pk_bf16_f32 v169, v169, v174
	s_nop 1
	v_permlane32_swap_b32_e32 v229, v230
	v_cvt_pk_bf16_f32 v170, v170, v173
	v_cvt_pk_bf16_f32 v171, v165, v171
	v_cvt_pk_bf16_f32 v172, v163, v172
	v_cvt_pk_bf16_f32 v173, v162, v164
	v_cvt_pk_bf16_f32 v174, v82, v83
	v_cvt_pk_bf16_f32 v175, v84, v85
	v_cvt_pk_bf16_f32 v176, v86, v87
	v_cvt_pk_bf16_f32 v177, v88, v89
	v_cvt_pk_bf16_f32 v178, v90, v91
	v_cvt_pk_bf16_f32 v179, v92, v93
	v_cvt_pk_bf16_f32 v180, v94, v95
	v_cvt_pk_bf16_f32 v181, v96, v97
	s_nop 0
	v_add_co_u32_e32 v86, vcc, s69, v190
	s_nop 1
	v_addc_co_u32_e32 v87, vcc, 0, v191, vcc
	v_add_co_u32_e32 v90, vcc, s74, v190
	s_nop 1
	v_addc_co_u32_e32 v91, vcc, 0, v191, vcc
	global_load_dwordx4 v[82:85], v[86:87], off offset:256
	s_nop 0
	global_load_dwordx4 v[86:89], v[86:87], off
	s_nop 0
	global_load_dwordx4 v[94:97], v[90:91], off offset:256
	s_nop 0
	global_load_dwordx4 v[90:93], v[90:91], off
	v_add_co_u32_e32 v162, vcc, s75, v196
	s_nop 1
	v_addc_co_u32_e32 v163, vcc, 0, v197, vcc
	global_load_dwordx4 v[162:165], v[162:163], off
	ds_read_b64_tr_b16 v[232:233], v208 offset:0
	ds_read_b64_tr_b16 v[234:235], v208 offset:0x800
	ds_read_b64_tr_b16 v[236:237], v208 offset:0x1000
	ds_read_b64_tr_b16 v[238:239], v208 offset:0x1800
	ds_read_b64_tr_b16 v[240:241], v208 offset:0x2000
	ds_read_b64_tr_b16 v[242:243], v208 offset:0x2800
	ds_read_b64_tr_b16 v[244:245], v208 offset:0x3000
	ds_read_b64_tr_b16 v[246:247], v208 offset:0x3800
	ds_read_b64_tr_b16 v[248:249], v208 offset:0x200
	ds_read_b64_tr_b16 v[250:251], v208 offset:0xa00
	s_waitcnt lgkmcnt(8)
; __device__ __forceinline__ void pv_d0(f32x16* o, int vb, bf16x8 pa0, bf16x8 pa1, bf16x8 pa2, bf16x8 pa3) {
;     ...
;   const s16x4 l0 = tr_read<v_rd_off(0, 0, 0)>(vb), h0 = tr_read<v_rd_off(0, 0, 1)>(vb);
;   const s16x4 l1 = tr_read<v_rd_off(0, 1, 0)>(vb), h1 = tr_read<v_rd_off(0, 1, 1)>(vb);
;   const s16x4 l2 = tr_read<v_rd_off(0, 2, 0)>(vb), h2 = tr_read<v_rd_off(0, 2, 1)>(vb);
;   const s16x4 l3 = tr_read<v_rd_off(0, 3, 0)>(vb), h3 = tr_read<v_rd_off(0, 3, 1)>(vb);
;   const s16x4 l4 = tr_read<v_rd_off(1, 0, 0)>(vb), h4 = tr_read<v_rd_off(1, 0, 1)>(vb);
;   asm volatile("s_waitcnt lgkmcnt(8)" ::: "memory"); SBAR();
;   o[0] = __builtin_amdgcn_mfma_f32_32x32x16_bf16(pa0, PK(l0, h0), o[0], 0, 0, 0);
;   const s16x4 l5 = tr_read<v_rd_off(1, 1, 0)>(vb), h5 = tr_read<v_rd_off(1, 1, 1)>(vb);
;   asm volatile("s_waitcnt lgkmcnt(8)" ::: "memory"); SBAR();
;   o[0] = __builtin_amdgcn_mfma_f32_32x32x16_bf16(pa1, PK(l1, h1), o[0], 0, 0, 0);
;   const s16x4 l6 = tr_read<v_rd_off(1, 2, 0)>(vb), h6 = tr_read<v_rd_off(1, 2, 1)>(vb);
;   asm volatile("s_waitcnt lgkmcnt(8)" ::: "memory"); SBAR();
;   o[0] = __builtin_amdgcn_mfma_f32_32x32x16_bf16(pa2, PK(l2, h2), o[0], 0, 0, 0);
;   const s16x4 l7 = tr_read<v_rd_off(1, 3, 0)>(vb), h7 = tr_read<v_rd_off(1, 3, 1)>(vb);
;   asm volatile("s_waitcnt lgkmcnt(8)" ::: "memory"); SBAR();
;   o[0] = __builtin_amdgcn_mfma_f32_32x32x16_bf16(pa3, PK(l3, h3), o[0], 0, 0, 0);
;   const s16x4 l8 = tr_read<v_rd_off(2, 0, 0)>(vb), h8 = tr_read<v_rd_off(2, 0, 1)>(vb);
;   asm volatile("s_waitcnt lgkmcnt(8)" ::: "memory"); SBAR();
;   o[1] = __builtin_amdgcn_mfma_f32_32x32x16_bf16(pa0, PK(l4, h4), o[1], 0, 0, 0);
;   const s16x4 l9 = tr_read<v_rd_off(2, 1, 0)>(vb), h9 = tr_read<v_rd_off(2, 1, 1)>(vb);
;   asm volatile("s_waitcnt lgkmcnt(8)" ::: "memory"); SBAR();
;   o[1] = __builtin_amdgcn_mfma_f32_32x32x16_bf16(pa1, PK(l5, h5), o[1], 0, 0, 0);
;   const s16x4 l10 = tr_read<v_rd_off(2, 2, 0)>(vb), h10 = tr_read<v_rd_off(2, 2, 1)>(vb);
;   asm volatile("s_waitcnt lgkmcnt(8)" ::: "memory"); SBAR();
;   o[1] = __builtin_amdgcn_mfma_f32_32x32x16_bf16(pa2, PK(l6, h6), o[1], 0, 0, 0);
;   const s16x4 l11 = tr_read<v_rd_off(2, 3, 0)>(vb), h11 = tr_read<v_rd_off(2, 3, 1)>(vb);
;   asm volatile("s_waitcnt lgkmcnt(8)" ::: "memory"); SBAR();
;   o[1] = __builtin_amdgcn_mfma_f32_32x32x16_bf16(pa3, PK(l7, h7), o[1], 0, 0, 0);
	s_nop 0
	v_mfma_f32_32x32x16_bf16 v[2:17], v[166:169], v[232:235], v[2:17]
	ds_read_b64_tr_b16 v[232:233], v208 offset:0x1200
	ds_read_b64_tr_b16 v[234:235], v208 offset:0x1a00
	s_waitcnt lgkmcnt(8)
	v_mfma_f32_32x32x16_bf16 v[2:17], v[170:173], v[236:239], v[2:17]
	ds_read_b64_tr_b16 v[236:237], v208 offset:0x2200
	ds_read_b64_tr_b16 v[238:239], v208 offset:0x2a00
	s_waitcnt lgkmcnt(8)
	v_mfma_f32_32x32x16_bf16 v[2:17], v[174:177], v[240:243], v[2:17]
	ds_read_b64_tr_b16 v[240:241], v208 offset:0x3200
	ds_read_b64_tr_b16 v[242:243], v208 offset:0x3a00
	s_waitcnt lgkmcnt(8)
	v_mfma_f32_32x32x16_bf16 v[2:17], v[178:181], v[244:247], v[2:17]
	ds_read_b64_tr_b16 v[244:245], v208 offset:0x400
	ds_read_b64_tr_b16 v[246:247], v208 offset:0xc00
	s_waitcnt lgkmcnt(8)
	v_mfma_f32_32x32x16_bf16 v[50:65], v[166:169], v[248:251], v[50:65]
	ds_read_b64_tr_b16 v[248:249], v208 offset:0x1400
	ds_read_b64_tr_b16 v[250:251], v208 offset:0x1c00
	s_waitcnt lgkmcnt(8)
	v_mfma_f32_32x32x16_bf16 v[50:65], v[170:173], v[232:235], v[50:65]
	ds_read_b64_tr_b16 v[232:233], v208 offset:0x2400
	ds_read_b64_tr_b16 v[234:235], v208 offset:0x2c00
	s_waitcnt lgkmcnt(8)
	v_mfma_f32_32x32x16_bf16 v[50:65], v[174:177], v[236:239], v[50:65]
	ds_read_b64_tr_b16 v[236:237], v208 offset:0x3400
	ds_read_b64_tr_b16 v[238:239], v208 offset:0x3c00
	s_waitcnt lgkmcnt(8)
	v_mfma_f32_32x32x16_bf16 v[50:65], v[178:181], v[240:243], v[50:65]
	ds_read_b64_tr_b16 v[240:241], v208 offset:0x600
	ds_read_b64_tr_b16 v[242:243], v208 offset:0xe00
	s_waitcnt lgkmcnt(8)
	v_mfma_f32_32x32x16_bf16 v[34:49], v[166:169], v[244:247], v[34:49]
	ds_read_b64_tr_b16 v[244:245], v208 offset:0x1600
	ds_read_b64_tr_b16 v[246:247], v208 offset:0x1e00
	s_waitcnt lgkmcnt(8)
	v_mfma_f32_32x32x16_bf16 v[34:49], v[170:173], v[248:251], v[34:49]
	ds_read_b64_tr_b16 v[248:249], v208 offset:0x2600
	ds_read_b64_tr_b16 v[250:251], v208 offset:0x2e00
	s_waitcnt lgkmcnt(8)
	v_mfma_f32_32x32x16_bf16 v[34:49], v[174:177], v[232:235], v[34:49]
	ds_read_b64_tr_b16 v[232:233], v208 offset:0x3600
	ds_read_b64_tr_b16 v[234:235], v208 offset:0x3e00
	s_waitcnt lgkmcnt(8)
	v_mfma_f32_32x32x16_bf16 v[34:49], v[178:181], v[236:239], v[34:49]
	s_waitcnt lgkmcnt(6)
	v_mfma_f32_32x32x16_bf16 v[18:33], v[166:169], v[240:243], v[18:33]
	s_waitcnt lgkmcnt(4)
	v_mfma_f32_32x32x16_bf16 v[18:33], v[170:173], v[244:247], v[18:33]
	s_waitcnt lgkmcnt(2)
	v_mfma_f32_32x32x16_bf16 v[18:33], v[174:177], v[248:251], v[18:33]
	s_waitcnt lgkmcnt(0)
	v_max_f32_e32 v166, v114, v118
	v_max_f32_e32 v167, v115, v119
	v_max_f32_e32 v168, v117, v121
	v_max3_f32 v169, v116, v120, v124
	v_max3_f32 v168, v168, v125, v129
	v_max3_f32 v166, v166, v122, v126
	v_max3_f32 v167, v167, v123, v127
	v_max3_f32 v169, v169, v128, v68
	v_max3_f32 v168, v168, v69, v73
	v_max3_f32 v166, v166, v66, v70
	v_max3_f32 v167, v167, v67, v71
	v_max3_f32 v169, v169, v72, v76
	v_max3_f32 v168, v168, v77, v81
	v_mfma_f32_32x32x16_bf16 v[18:33], v[178:181], v[232:235], v[18:33]
	v_max3_f32 v166, v166, v74, v78
	v_max3_f32 v167, v167, v75, v79
	v_max3_f32 v168, v169, v80, v168
	v_max3_f32 v166, v166, v167, v168
	v_mov_b32_e32 v167, v166
	v_cmp_ge_f32_e32 vcc, s48, v167
	s_cmp_eq_u64 vcc, exec
	v_mov_b32_e32 v166, 1.0
	s_cbranch_scc0 .LBB0_401
	v_mov_b32_e32 v225, v227
